# one static s_setprio 1 at kernel entry for the second workgroup on each CU (LDS base != 0), nothing else changed vs write-through version
# baseline (speedup 1.0000x reference)
_Z11mega_kernel6Params:
	v_and_b32_e32 v179, 0x3ff, v0
	s_getreg_b32 s100, hwreg(HW_REG_LDS_ALLOC, 0, 8)
	s_cmp_eq_u32 s100, 0
	s_cbranch_scc1 .Lprio_done
	s_setprio 1
.Lprio_done:
	v_writelane_b32 v253, s2, 0
	s_load_dwordx8 s[44:51], s[0:1], 0x140
	s_load_dword s2, s[0:1], 0x170
	v_cmp_eq_u32_e32 vcc, 0, v179
	s_waitcnt lgkmcnt(0)
	v_writelane_b32 v253, s2, 1
	s_add_u32 s2, s0, 0x170
	s_addc_u32 s3, s1, 0
	s_and_saveexec_b64 s[4:5], vcc
	s_cbranch_execz .LBB0_3
	s_mov_b64 s[6:7], exec
	v_mbcnt_lo_u32_b32 v1, s6, 0
	v_mov_b32_e32 v2, 0
	v_mbcnt_hi_u32_b32 v1, s7, v1
	v_mov_b32_e32 v3, v2
	v_cmp_eq_u32_e32 vcc, 0, v1
	ds_write_b64 v2, v[2:3] offset:65056
	s_getreg_b32 s8, hwreg(HW_REG_XCC_ID, 0, 4)
	s_and_b64 s[10:11], exec, vcc
	s_mov_b64 exec, s[10:11]
	s_cbranch_execz .LBB0_3
	s_lshl_b32 s8, s8, 8
	s_and_b32 s8, s8, 0xf00
	s_bcnt1_i32_b64 s6, s[6:7]
	v_mov_b32_e32 v1, s8
	v_mov_b32_e32 v2, s6
	global_atomic_add v1, v2, s[50:51] offset:256
